# adds: prep2 q-row loads hoisted next to the kv loads (one HBM round trip per token instead of two)
# speedup vs baseline: 1.0067x; 1.0067x over previous
.LBB0_700:
	v_lshl_add_u64 v[16:17], s[50:51], 0, v[36:37]
	s_mov_b64 s[4:5], 0xe8a2000
	v_lshl_add_u64 v[12:13], v[16:17], 0, s[4:5]
	v_add_co_u32_e32 v16, vcc, 0xe8a2000, v16
	global_load_dwordx4 v[12:15], v[12:13], off offset:16 nt
	s_nop 0
	v_addc_co_u32_e32 v17, vcc, 0, v17, vcc
	global_load_dwordx4 v[16:19], v[16:17], off nt
	v_lshl_add_u64 v[100:101], s[50:51], 0, v[34:35]
	global_load_dwordx4 v[102:105], v[100:101], off nt
	v_lshl_add_u64 v[100:101], s[50:51], 0, v[32:33]
	global_load_dwordx2 v[106:107], v[100:101], off nt
	s_waitcnt vmcnt(3)
	v_lshlrev_b32_e32 v38, 16, v12
	v_and_b32_e32 v39, 0xffff0000, v12
	v_lshlrev_b32_e32 v40, 16, v13
	v_and_b32_e32 v41, 0xffff0000, v13
	v_lshlrev_b32_e32 v42, 16, v14
	v_and_b32_e32 v43, 0xffff0000, v14
	v_pk_mul_f32 v[62:63], v[38:39], v[38:39]
	v_pk_mul_f32 v[64:65], v[40:41], v[40:41]
	s_waitcnt vmcnt(2)
	v_lshlrev_b32_e32 v52, 16, v16
	v_and_b32_e32 v53, 0xffff0000, v16
	v_lshlrev_b32_e32 v50, 16, v17
	v_and_b32_e32 v51, 0xffff0000, v17
	v_pk_mul_f32 v[66:67], v[42:43], v[42:43]
	v_lshlrev_b32_e32 v48, 16, v18
	v_and_b32_e32 v49, 0xffff0000, v18
	v_add_f32_e32 v61, v62, v63
	v_add_f32_e32 v72, v64, v65
	v_pk_mul_f32 v[62:63], v[52:53], v[52:53]
	v_pk_mul_f32 v[64:65], v[50:51], v[50:51]
	v_lshlrev_b32_e32 v46, 16, v19
	v_and_b32_e32 v47, 0xffff0000, v19
	v_add_f32_e32 v73, v66, v67
	v_pk_mul_f32 v[66:67], v[48:49], v[48:49]
	v_add_f32_e32 v64, v64, v65
	v_add_f32_e32 v62, v62, v63
	v_pk_mul_f32 v[70:71], v[46:47], v[46:47]
	v_add_f32_e32 v63, v66, v67
	v_add_f32_e32 v62, v62, v64
	v_add_f32_e32 v70, v70, v71
	v_add_f32_e32 v62, v63, v62
	v_add_f32_e32 v62, v70, v62
	v_lshlrev_b32_e32 v44, 16, v15
	v_and_b32_e32 v45, 0xffff0000, v15
	v_add_f32_e32 v61, v61, v62
	v_pk_mul_f32 v[68:69], v[44:45], v[44:45]
	v_add_f32_e32 v61, v72, v61
	v_add_f32_e32 v61, v73, v61
	v_add_f32_e32 v62, v68, v69
	v_add_f32_e32 v61, v62, v61
	ds_bpermute_b32 v62, v56, v61
	s_waitcnt lgkmcnt(0)
	v_add_f32_e32 v62, v61, v62
	ds_bpermute_b32 v63, v57, v62
	v_lshl_or_b32 v61, s10, 3, v1
	s_and_saveexec_b64 s[4:5], s[2:3]
	s_xor_b64 s[4:5], exec, s[4:5]
	s_cbranch_execz .LBB0_702
	v_mov_b32_e32 v38, s9
	v_mov_b32_e32 v39, v0
	v_mad_i64_i32 v[38:39], s[10:11], v61, s64, v[38:39]
	v_lshlrev_b64 v[38:39], 7, v[38:39]
	v_lshl_add_u64 v[38:39], v[20:21], 0, v[38:39]
	global_store_dwordx4 v[38:39], v[16:19], off offset:-128
	global_store_dwordx4 v[38:39], v[12:15], off offset:-112

.LBB0_704:
	s_or_b64 exec, exec, s[4:5]
	s_waitcnt vmcnt(2)
	v_mov_b32_e32 v12, v102
	v_mov_b32_e32 v13, v103
	v_mov_b32_e32 v14, v104
	v_mov_b32_e32 v15, v105
	v_mov_b32_e32 v44, v106
	v_mov_b32_e32 v45, v107
	s_mov_b32 s4, 0x3d000000
	s_mov_b32 s5, 0x3c800000
	v_lshl_add_u64 v[42:43], s[50:51], 0, v[30:31]
	v_and_b32_e32 v41, 0xffff0000, v12
	v_and_b32_e32 v19, 0xffff0000, v15
	v_and_b32_e32 v18, s0, v14
	v_lshlrev_b32_e32 v40, 16, v12
	v_mul_f32_e32 v12, v41, v41
	v_lshlrev_b32_e32 v16, 16, v15
	v_mov_b32_e32 v17, v19
	v_pk_mul_f32 v[18:19], v[18:19], v[18:19]
	v_lshlrev_b32_e32 v38, 16, v14
	v_and_b32_e32 v39, 0xffff0000, v14
	v_lshlrev_b32_e32 v14, 16, v13
	v_and_b32_e32 v15, 0xffff0000, v13
	v_pk_fma_f32 v[12:13], v[40:41], v[40:41], v[12:13] op_sel_hi:[1,1,0]
	v_mul_f32_e32 v18, v15, v15
	v_pk_fma_f32 v[12:13], v[14:15], v[14:15], v[12:13]
	v_lshlrev_b32_e32 v47, 16, v45
	v_pk_add_f32 v[12:13], v[18:19], v[12:13] op_sel_hi:[0,1]
	v_pk_fma_f32 v[12:13], v[38:39], v[38:39], v[12:13]
	v_mul_f32_e32 v18, v39, v39
	v_lshlrev_b32_e32 v46, 16, v44
	v_and_b32_e32 v45, 0xffff0000, v45
	v_and_b32_e32 v44, 0xffff0000, v44
	v_pk_add_f32 v[12:13], v[18:19], v[12:13] op_sel_hi:[0,1]
	v_pk_mul_f32 v[48:49], v[44:45], v[44:45]
	v_pk_fma_f32 v[12:13], v[16:17], v[16:17], v[12:13]
	v_pk_fma_f32 v[48:49], v[46:47], v[46:47], v[48:49]
	s_nop 0
	v_mov_b32_e32 v18, v48
	v_pk_mov_b32 v[12:13], v[48:49], v[12:13] op_sel:[1,0]
	s_nop 0
	v_pk_add_f32 v[12:13], v[18:19], v[12:13]
	ds_bpermute_b32 v19, v56, v13
	ds_bpermute_b32 v18, v56, v12
	s_waitcnt lgkmcnt(0)
	v_pk_add_f32 v[12:13], v[12:13], v[18:19]
	ds_bpermute_b32 v19, v57, v13
	ds_bpermute_b32 v18, v57, v12
	s_waitcnt lgkmcnt(0)
	v_pk_add_f32 v[12:13], v[12:13], v[18:19]
	ds_bpermute_b32 v19, v58, v13
	ds_bpermute_b32 v18, v58, v12
	s_waitcnt lgkmcnt(0)
	v_pk_add_f32 v[12:13], v[12:13], v[18:19]
	s_nop 0
	v_pk_fma_f32 v[18:19], v[12:13], s[4:5], v[206:207] op_sel_hi:[1,1,0]
	s_nop 0
	v_mul_f32_e32 v12, 0x4b800000, v19
	v_cmp_gt_f32_e64 s[4:5], s97, v19
	v_cmp_gt_f32_e32 vcc, s97, v18
	s_nop 0
	v_cndmask_b32_e64 v12, v19, v12, s[4:5]
	v_rsq_f32_e32 v12, v12
	s_nop 0
	v_mul_f32_e32 v13, 0x45800000, v12
	v_cndmask_b32_e64 v12, v12, v13, s[4:5]
	v_mul_f32_e32 v48, 0x3e16c740, v12
	v_pk_mul_f32 v[12:13], v[48:49], v[40:41] op_sel_hi:[0,1]
	v_pk_mul_f32 v[14:15], v[48:49], v[14:15] op_sel_hi:[0,1]
	v_pk_mul_f32 v[12:13], v[2:3], v[12:13]
	v_pk_mul_f32 v[14:15], v[4:5], v[14:15]
	v_cvt_pk_bf16_f32 v12, v12, v13
	v_cvt_pk_bf16_f32 v13, v14, v15
	v_pk_mul_f32 v[14:15], v[48:49], v[38:39] op_sel_hi:[0,1]
	v_pk_mul_f32 v[16:17], v[48:49], v[16:17] op_sel_hi:[0,1]
	v_pk_mul_f32 v[14:15], v[6:7], v[14:15]
	v_pk_mul_f32 v[16:17], v[8:9], v[16:17]
	v_cvt_pk_bf16_f32 v14, v14, v15
	v_cvt_pk_bf16_f32 v15, v16, v17
	global_store_dwordx4 v[42:43], v[12:15], off
	s_nop 1
	v_mul_f32_e32 v12, 0x4b800000, v18
	v_cndmask_b32_e32 v12, v18, v12, vcc
	v_rsq_f32_e32 v12, v12
	s_nop 0
	v_mul_f32_e32 v13, 0x45800000, v12
	v_cndmask_b32_e32 v12, v12, v13, vcc
	v_pk_mul_f32 v[14:15], v[10:11], v[12:13] op_sel_hi:[1,0]
	v_pk_mul_f32 v[12:13], v[26:27], v[12:13] op_sel_hi:[1,0]
	v_pk_mul_f32 v[14:15], v[14:15], v[46:47]
	v_pk_mul_f32 v[12:13], v[12:13], v[44:45]
	s_andn2_b64 vcc, exec, s[6:7]
	s_cbranch_vccnz .LBB0_695
	v_cndmask_b32_e64 v17, v60, v59, s[0:1]
	v_mul_f32_e32 v16, v54, v17
	v_mul_f32_e32 v17, v55, v17
	v_mul_f32_e32 v18, 0.15915494, v16
	v_mul_f32_e32 v19, 0.15915494, v17
	v_sin_f32_e32 v16, v18
	v_sin_f32_e32 v17, v19
	v_cos_f32_e32 v18, v18
	v_cos_f32_e32 v19, v19
	v_pk_mul_f32 v[38:39], v[16:17], v[12:13]
	s_nop 0
	v_pk_fma_f32 v[38:39], v[18:19], v[14:15], v[38:39] neg_lo:[0,0,1] neg_hi:[0,0,1]
	v_pk_mul_f32 v[12:13], v[18:19], v[12:13]
	s_nop 0
	v_pk_fma_f32 v[12:13], v[16:17], v[14:15], v[12:13]
	v_mov_b64_e32 v[14:15], v[38:39]
	s_branch .LBB0_695
